# prologue converter bf16 weight stores with nt hint, on top of packed norm + hand-written converter
# speedup vs baseline: 1.0013x; 1.0013x over previous
; #define LAS __attribute__((address_space(3)))
; #define LDS_WAIT() asm volatile("s_waitcnt lgkmcnt(0)" ::: "memory")
; __device__ __forceinline__ unsigned pk2(float lo, float hi) { const f32x2c v = {lo, hi}; return __builtin_bit_cast(unsigned, __builtin_convertvector(v, bf16x2c)); }
; __device__ __forceinline__ void tr_store(bf16* dst, int K, const LAS float* scr, int lane) {
;     const int c = lane & 7;
; #pragma unroll
;     for (int j = 0; j < 8; ++j) { const int n = (lane >> 3) + 8 * j; const LAS float* s = scr + (8 * c) * 65 + n;
;         v4u o; o.x = pk2(s[0], s[65]); o.y = pk2(s[130], s[195]); o.z = pk2(s[260], s[325]); o.w = pk2(s[390], s[455]);
;         *(v4u*)(dst + (size_t)n * K + 8 * c) = o; }
;     LDS_WAIT(); asm volatile("" ::: "memory");
; __device__ __forceinline__ void convert_segments(const Args& args, unsigned char* ws, LAS unsigned char* lds, int seg_lo, int seg_hi, int part_lo, int part_hi, int nparts, int wid, int nw, int wave, int lane) {
;     ...
;             const int kb = it / nblk, nb = it - kb * nblk;
;             const int drow = sg.ilv ? (256 * (nb >> 1) + 64 * (nb & 1) + sg.drow) : (sg.drow + 64 * nb);
;             tr_to_lds(v, scr, lane);
;             const int itn = it + nw;
;             if (itn < it_hi) { const int kbn = itn / nblk, nbn = itn - kbn * nblk; tr_load(W + (size_t)(64 * kbn) * sg.N + sg.scol + 64 * nbn, sg.N, v, lane); }
;             tr_store(WT + (size_t)drow * sg.K + 64 * kb, sg.K, scr, lane);
cvp_nlA:
	s_lshr_b32 s4, s53, 1
	s_lshl_b32 s4, s4, 8
	s_and_b32 s5, s53, 1
	s_lshl_b32 s5, s5, 6
	s_add_i32 s4, s4, s5
	s_lshl_b32 s5, s53, 6
	s_cmp_lg_u32 s19, 0
	s_cselect_b32 s4, s4, s5
	s_add_i32 s4, s4, s18
	s_mul_i32 s4, s4, s11
	s_lshl_b32 s5, s52, 6
	s_add_i32 s4, s4, s5
	s_lshl_b32 s4, s4, 1
	s_add_u32 s54, s26, s4
	s_addc_u32 s55, s27, 0
	ds_read2_b32 v[128:129], v166 offset0:0 offset1:65
	ds_read2_b32 v[130:131], v166 offset0:130 offset1:195
	ds_read2_b32 v[132:133], v167 offset0:0 offset1:65
	ds_read2_b32 v[134:135], v167 offset0:130 offset1:195
	ds_read2_b32 v[136:137], v166 offset0:8 offset1:73
	ds_read2_b32 v[138:139], v166 offset0:138 offset1:203
	ds_read2_b32 v[140:141], v167 offset0:8 offset1:73
	ds_read2_b32 v[142:143], v167 offset0:138 offset1:203
	s_waitcnt lgkmcnt(4)
	v_cvt_pk_bf16_f32 v152, v128, v129
	v_cvt_pk_bf16_f32 v153, v130, v131
	v_cvt_pk_bf16_f32 v154, v132, v133
	v_cvt_pk_bf16_f32 v155, v134, v135
	global_store_dwordx4 v169, v[152:155], s[54:55] nt
	s_add_u32 s54, s54, s49
	s_addc_u32 s55, s55, 0
	ds_read2_b32 v[144:145], v166 offset0:16 offset1:81
	ds_read2_b32 v[146:147], v166 offset0:146 offset1:211
	ds_read2_b32 v[148:149], v167 offset0:16 offset1:81
	ds_read2_b32 v[150:151], v167 offset0:146 offset1:211
	s_waitcnt lgkmcnt(4)
	v_cvt_pk_bf16_f32 v156, v136, v137
	v_cvt_pk_bf16_f32 v157, v138, v139
	v_cvt_pk_bf16_f32 v158, v140, v141
	v_cvt_pk_bf16_f32 v159, v142, v143
	global_store_dwordx4 v169, v[156:159], s[54:55] nt
	s_add_u32 s54, s54, s49
	s_addc_u32 s55, s55, 0
	ds_read2_b32 v[128:129], v166 offset0:24 offset1:89
	ds_read2_b32 v[130:131], v166 offset0:154 offset1:219
	ds_read2_b32 v[132:133], v167 offset0:24 offset1:89
	ds_read2_b32 v[134:135], v167 offset0:154 offset1:219
	s_waitcnt lgkmcnt(4)
	v_cvt_pk_bf16_f32 v152, v144, v145
	v_cvt_pk_bf16_f32 v153, v146, v147
	v_cvt_pk_bf16_f32 v154, v148, v149
	v_cvt_pk_bf16_f32 v155, v150, v151
	global_store_dwordx4 v169, v[152:155], s[54:55] nt
	s_add_u32 s54, s54, s49
	s_addc_u32 s55, s55, 0
	ds_read2_b32 v[136:137], v166 offset0:32 offset1:97
	ds_read2_b32 v[138:139], v166 offset0:162 offset1:227
	ds_read2_b32 v[140:141], v167 offset0:32 offset1:97
	ds_read2_b32 v[142:143], v167 offset0:162 offset1:227
	s_waitcnt lgkmcnt(4)
	v_cvt_pk_bf16_f32 v156, v128, v129
	v_cvt_pk_bf16_f32 v157, v130, v131
	v_cvt_pk_bf16_f32 v158, v132, v133
	v_cvt_pk_bf16_f32 v159, v134, v135
	global_store_dwordx4 v169, v[156:159], s[54:55] nt
	s_add_u32 s54, s54, s49
	s_addc_u32 s55, s55, 0
	ds_read2_b32 v[144:145], v166 offset0:40 offset1:105
	ds_read2_b32 v[146:147], v166 offset0:170 offset1:235
	ds_read2_b32 v[148:149], v167 offset0:40 offset1:105
	ds_read2_b32 v[150:151], v167 offset0:170 offset1:235
	s_waitcnt lgkmcnt(4)
	v_cvt_pk_bf16_f32 v152, v136, v137
	v_cvt_pk_bf16_f32 v153, v138, v139
	v_cvt_pk_bf16_f32 v154, v140, v141
	v_cvt_pk_bf16_f32 v155, v142, v143
	global_store_dwordx4 v169, v[152:155], s[54:55] nt
	s_add_u32 s54, s54, s49
	s_addc_u32 s55, s55, 0
	ds_read2_b32 v[128:129], v166 offset0:48 offset1:113
	ds_read2_b32 v[130:131], v166 offset0:178 offset1:243
	ds_read2_b32 v[132:133], v167 offset0:48 offset1:113
	ds_read2_b32 v[134:135], v167 offset0:178 offset1:243
	s_waitcnt lgkmcnt(4)
	v_cvt_pk_bf16_f32 v156, v144, v145
	v_cvt_pk_bf16_f32 v157, v146, v147
	v_cvt_pk_bf16_f32 v158, v148, v149
	v_cvt_pk_bf16_f32 v159, v150, v151
	global_store_dwordx4 v169, v[156:159], s[54:55] nt
	s_add_u32 s54, s54, s49
	s_addc_u32 s55, s55, 0
	ds_read2_b32 v[136:137], v166 offset0:56 offset1:121
	ds_read2_b32 v[138:139], v166 offset0:186 offset1:251
	ds_read2_b32 v[140:141], v167 offset0:56 offset1:121
	ds_read2_b32 v[142:143], v167 offset0:186 offset1:251
	s_waitcnt lgkmcnt(4)
	v_cvt_pk_bf16_f32 v152, v128, v129
	v_cvt_pk_bf16_f32 v153, v130, v131
	v_cvt_pk_bf16_f32 v154, v132, v133
	v_cvt_pk_bf16_f32 v155, v134, v135
	global_store_dwordx4 v169, v[152:155], s[54:55] nt
	s_add_u32 s54, s54, s49
	s_addc_u32 s55, s55, 0
	s_waitcnt lgkmcnt(0)
	v_cvt_pk_bf16_f32 v156, v136, v137
	v_cvt_pk_bf16_f32 v157, v138, v139
	v_cvt_pk_bf16_f32 v158, v140, v141
	v_cvt_pk_bf16_f32 v159, v142, v143
	global_store_dwordx4 v169, v[156:159], s[54:55] nt
	s_add_i32 s51, s51, s63
	s_add_i32 s53, s53, s45
	s_add_i32 s52, s52, s44
	s_cmp_ge_u32 s53, s20
	s_cselect_b32 s4, s20, 0
	s_cselect_b32 s5, 1, 0
	s_sub_i32 s53, s53, s4
	s_add_i32 s52, s52, s5
	s_cmp_lt_i32 s51, s42
	s_cbranch_scc0 cvp_next

; #define LAS __attribute__((address_space(3)))
; #define LDS_WAIT() asm volatile("s_waitcnt lgkmcnt(0)" ::: "memory")
; __device__ __forceinline__ unsigned pk2(float lo, float hi) { const f32x2c v = {lo, hi}; return __builtin_bit_cast(unsigned, __builtin_convertvector(v, bf16x2c)); }
; __device__ __forceinline__ void tr_store(bf16* dst, int K, const LAS float* scr, int lane) {
;     const int c = lane & 7;
; #pragma unroll
;     for (int j = 0; j < 8; ++j) { const int n = (lane >> 3) + 8 * j; const LAS float* s = scr + (8 * c) * 65 + n;
;         v4u o; o.x = pk2(s[0], s[65]); o.y = pk2(s[130], s[195]); o.z = pk2(s[260], s[325]); o.w = pk2(s[390], s[455]);
;         *(v4u*)(dst + (size_t)n * K + 8 * c) = o; }
;     LDS_WAIT(); asm volatile("" ::: "memory");
; __device__ __forceinline__ void convert_segments(const Args& args, unsigned char* ws, LAS unsigned char* lds, int seg_lo, int seg_hi, int part_lo, int part_hi, int nparts, int wid, int nw, int wave, int lane) {
;     ...
;             const int kb = it / nblk, nb = it - kb * nblk;
;             const int drow = sg.ilv ? (256 * (nb >> 1) + 64 * (nb & 1) + sg.drow) : (sg.drow + 64 * nb);
;             tr_to_lds(v, scr, lane);
;             const int itn = it + nw;
;             if (itn < it_hi) { const int kbn = itn / nblk, nbn = itn - kbn * nblk; tr_load(W + (size_t)(64 * kbn) * sg.N + sg.scol + 64 * nbn, sg.N, v, lane); }
;             tr_store(WT + (size_t)drow * sg.K + 64 * kb, sg.K, scr, lane);
cvp_nlB:
	s_lshr_b32 s4, s53, 1
	s_lshl_b32 s4, s4, 8
	s_and_b32 s5, s53, 1
	s_lshl_b32 s5, s5, 6
	s_add_i32 s4, s4, s5
	s_lshl_b32 s5, s53, 6
	s_cmp_lg_u32 s19, 0
	s_cselect_b32 s4, s4, s5
	s_add_i32 s4, s4, s18
	s_mul_i32 s4, s4, s11
	s_lshl_b32 s5, s52, 6
	s_add_i32 s4, s4, s5
	s_lshl_b32 s4, s4, 1
	s_add_u32 s54, s26, s4
	s_addc_u32 s55, s27, 0
	ds_read2_b32 v[128:129], v166 offset0:0 offset1:65
	ds_read2_b32 v[130:131], v166 offset0:130 offset1:195
	ds_read2_b32 v[132:133], v167 offset0:0 offset1:65
	ds_read2_b32 v[134:135], v167 offset0:130 offset1:195
	ds_read2_b32 v[136:137], v166 offset0:8 offset1:73
	ds_read2_b32 v[138:139], v166 offset0:138 offset1:203
	ds_read2_b32 v[140:141], v167 offset0:8 offset1:73
	ds_read2_b32 v[142:143], v167 offset0:138 offset1:203
	s_waitcnt lgkmcnt(4)
	v_cvt_pk_bf16_f32 v152, v128, v129
	v_cvt_pk_bf16_f32 v153, v130, v131
	v_cvt_pk_bf16_f32 v154, v132, v133
	v_cvt_pk_bf16_f32 v155, v134, v135
	global_store_dwordx4 v169, v[152:155], s[54:55] nt
	s_add_u32 s54, s54, s49
	s_addc_u32 s55, s55, 0
	ds_read2_b32 v[144:145], v166 offset0:16 offset1:81
	ds_read2_b32 v[146:147], v166 offset0:146 offset1:211
	ds_read2_b32 v[148:149], v167 offset0:16 offset1:81
	ds_read2_b32 v[150:151], v167 offset0:146 offset1:211
	s_waitcnt lgkmcnt(4)
	v_cvt_pk_bf16_f32 v156, v136, v137
	v_cvt_pk_bf16_f32 v157, v138, v139
	v_cvt_pk_bf16_f32 v158, v140, v141
	v_cvt_pk_bf16_f32 v159, v142, v143
	global_store_dwordx4 v169, v[156:159], s[54:55] nt
	s_add_u32 s54, s54, s49
	s_addc_u32 s55, s55, 0
	ds_read2_b32 v[128:129], v166 offset0:24 offset1:89
	ds_read2_b32 v[130:131], v166 offset0:154 offset1:219
	ds_read2_b32 v[132:133], v167 offset0:24 offset1:89
	ds_read2_b32 v[134:135], v167 offset0:154 offset1:219
	s_waitcnt lgkmcnt(4)
	v_cvt_pk_bf16_f32 v152, v144, v145
	v_cvt_pk_bf16_f32 v153, v146, v147
	v_cvt_pk_bf16_f32 v154, v148, v149
	v_cvt_pk_bf16_f32 v155, v150, v151
	global_store_dwordx4 v169, v[152:155], s[54:55] nt
	s_add_u32 s54, s54, s49
	s_addc_u32 s55, s55, 0
	ds_read2_b32 v[136:137], v166 offset0:32 offset1:97
	ds_read2_b32 v[138:139], v166 offset0:162 offset1:227
	ds_read2_b32 v[140:141], v167 offset0:32 offset1:97
	ds_read2_b32 v[142:143], v167 offset0:162 offset1:227
	s_waitcnt lgkmcnt(4)
	v_cvt_pk_bf16_f32 v156, v128, v129
	v_cvt_pk_bf16_f32 v157, v130, v131
	v_cvt_pk_bf16_f32 v158, v132, v133
	v_cvt_pk_bf16_f32 v159, v134, v135
	global_store_dwordx4 v169, v[156:159], s[54:55] nt
	s_add_u32 s54, s54, s49
	s_addc_u32 s55, s55, 0
	ds_read2_b32 v[144:145], v166 offset0:40 offset1:105
	ds_read2_b32 v[146:147], v166 offset0:170 offset1:235
	ds_read2_b32 v[148:149], v167 offset0:40 offset1:105
	ds_read2_b32 v[150:151], v167 offset0:170 offset1:235
	s_waitcnt lgkmcnt(4)
	v_cvt_pk_bf16_f32 v152, v136, v137
	v_cvt_pk_bf16_f32 v153, v138, v139
	v_cvt_pk_bf16_f32 v154, v140, v141
	v_cvt_pk_bf16_f32 v155, v142, v143
	global_store_dwordx4 v169, v[152:155], s[54:55] nt
	s_add_u32 s54, s54, s49
	s_addc_u32 s55, s55, 0
	ds_read2_b32 v[128:129], v166 offset0:48 offset1:113
	ds_read2_b32 v[130:131], v166 offset0:178 offset1:243
	ds_read2_b32 v[132:133], v167 offset0:48 offset1:113
	ds_read2_b32 v[134:135], v167 offset0:178 offset1:243
	s_waitcnt lgkmcnt(4)
	v_cvt_pk_bf16_f32 v156, v144, v145
	v_cvt_pk_bf16_f32 v157, v146, v147
	v_cvt_pk_bf16_f32 v158, v148, v149
	v_cvt_pk_bf16_f32 v159, v150, v151
	global_store_dwordx4 v169, v[156:159], s[54:55] nt
	s_add_u32 s54, s54, s49
	s_addc_u32 s55, s55, 0
	ds_read2_b32 v[136:137], v166 offset0:56 offset1:121
	ds_read2_b32 v[138:139], v166 offset0:186 offset1:251
	ds_read2_b32 v[140:141], v167 offset0:56 offset1:121
	ds_read2_b32 v[142:143], v167 offset0:186 offset1:251
	s_waitcnt lgkmcnt(4)
	v_cvt_pk_bf16_f32 v152, v128, v129
	v_cvt_pk_bf16_f32 v153, v130, v131
	v_cvt_pk_bf16_f32 v154, v132, v133
	v_cvt_pk_bf16_f32 v155, v134, v135
	global_store_dwordx4 v169, v[152:155], s[54:55] nt
	s_add_u32 s54, s54, s49
	s_addc_u32 s55, s55, 0
	s_waitcnt lgkmcnt(0)
	v_cvt_pk_bf16_f32 v156, v136, v137
	v_cvt_pk_bf16_f32 v157, v138, v139
	v_cvt_pk_bf16_f32 v158, v140, v141
	v_cvt_pk_bf16_f32 v159, v142, v143
	global_store_dwordx4 v169, v[156:159], s[54:55] nt
	s_add_i32 s51, s51, s63
	s_add_i32 s53, s53, s45
	s_add_i32 s52, s52, s44
	s_cmp_ge_u32 s53, s20
	s_cselect_b32 s4, s20, 0
	s_cselect_b32 s5, 1, 0
	s_sub_i32 s53, s53, s4
	s_add_i32 s52, s52, s5
	s_cmp_lt_i32 s51, s42
	s_cbranch_scc0 cvp_next
	s_branch cvp_stepA
